# FFN-up phases: half patches moved to last round (blocks<256: 6 tiles, >=256: 5) + half-tile start stagger for blocks>=256
# speedup vs baseline: 1.0020x; 1.0020x over previous
.LBB0_963:
	v_mov_b32_e32 v252, 0
	ds_read_b64 v[250:251], v252
	s_waitcnt lgkmcnt(0)
	s_cmp_lt_i32 s84, 0
	s_cbranch_scc1 .LBB0_979
	s_bitcmp0_b32 s84, 8
	s_cbranch_scc1 .LBB0_966
	s_sleep 127
	s_sleep 127
	s_sleep 127
	s_sleep 64

.LBB0_970:
	s_ashr_i32 s4, s13, 6
	s_mul_i32 s8, s4, s11
	s_add_i32 s8, s8, s10
	s_cmp_gt_i32 s8, 47
	s_mov_b32 s34, 2
	s_cbranch_scc1 .LBB0_975
	s_cmp_lt_i32 s8, 40
	s_cbranch_scc0 .Lpm963_hi
	s_mul_hi_i32 s9, s8, 0x33333334
	s_mul_i32 s4, s9, 5
	s_sub_i32 s4, s8, s4
	s_branch .Lpm963_done
.Lpm963_hi:
	s_add_i32 s9, s8, 0xffffffd8
	s_mov_b32 s4, 5
.Lpm963_done:
	s_lshl_b32 s4, s4, 3
	s_bfe_u32 s33, s13, 0x30003
	s_or_b32 s6, s4, s33
	s_cmp_gt_i32 s6, 43
	s_mov_b32 s34, 4
	s_cbranch_scc1 .LBB0_975
	s_bfe_u32 s4, s14, 0x30005
	s_lshl_b32 s5, s13, 5
	s_mul_i32 s38, s4, 0xc0
	s_lshl_b32 s4, s9, 8
	s_and_b32 s5, s5, 0xe0
	s_or_b32 s4, s4, s5
	s_mul_i32 s4, s4, 6
	s_ashr_i32 s5, s4, 31
	s_lshl_b64 s[34:35], s[4:5], 11
	v_lshl_add_u64 v[0:1], v[136:137], 0, s[34:35]
	v_add_co_u32_e32 v2, vcc, s16, v0
	s_lshl_b32 s6, s6, 7
	s_nop 0
	v_addc_co_u32_e32 v3, vcc, 0, v1, vcc
	s_nop 0
	v_readfirstlane_b32 s98, v0
	v_readfirstlane_b32 s99, v1
	v_add_co_u32_e32 v2, vcc, s17, v0
	s_ashr_i32 s7, s6, 31
	s_nop 0
	v_addc_co_u32_e32 v3, vcc, 0, v1, vcc
	v_add_co_u32_e32 v4, vcc, s18, v0
	s_lshl_b64 s[36:37], s[6:7], 11
	s_nop 0
	v_addc_co_u32_e32 v5, vcc, 0, v1, vcc
	v_add_co_u32_e32 v2, vcc, s19, v0
	s_mul_i32 s5, s9, 0x600
	s_nop 0
	v_addc_co_u32_e32 v3, vcc, 0, v1, vcc
	v_add_co_u32_e32 v0, vcc, s20, v0
	s_add_i32 s34, s5, s38
	s_nop 0
	v_addc_co_u32_e32 v1, vcc, 0, v1, vcc
	v_lshl_add_u64 v[0:1], v[138:139], 0, s[36:37]
	v_add_co_u32_e32 v2, vcc, s16, v0
	s_lshl_b32 s5, s8, 3
	s_nop 0
	v_addc_co_u32_e32 v3, vcc, 0, v1, vcc
	s_nop 0
	v_readfirstlane_b32 s100, v0
	v_readfirstlane_b32 s101, v1
	v_add_co_u32_e32 v2, vcc, s17, v0
	s_or_b32 s5, s5, s33
	s_nop 0
	v_addc_co_u32_e32 v3, vcc, 0, v1, vcc
	v_add_co_u32_e32 v0, vcc, s18, v0
	s_mul_i32 s9, s9, 48
	s_nop 0
	v_addc_co_u32_e32 v1, vcc, 0, v1, vcc
	s_sub_i32 s5, s5, s9
	s_lshl_b32 s8, s5, 7
	s_ashr_i32 s35, s34, 31
	s_ashr_i32 s9, s8, 31
	s_lshl_b64 s[34:35], s[34:35], 11
	s_lshl_b64 s[8:9], s[8:9], 11
	v_mov_b32_e32 v60, 0
	v_lshl_add_u64 v[142:143], v[140:141], 0, s[34:35]
	v_lshl_add_u64 v[144:145], v[140:141], 0, s[8:9]
	s_mov_b64 s[8:9], 0
	v_mov_b32_e32 v61, v60
	v_mov_b32_e32 v62, v60
	v_mov_b32_e32 v63, v60
	v_mov_b32_e32 v0, v60
	v_mov_b32_e32 v1, v60
	v_mov_b32_e32 v2, v60
	v_mov_b32_e32 v3, v60
	v_mov_b32_e32 v4, v60
	v_mov_b32_e32 v5, v60
	v_mov_b32_e32 v6, v60
	v_mov_b32_e32 v7, v60
	v_mov_b32_e32 v8, v60
	v_mov_b32_e32 v9, v60
	v_mov_b32_e32 v10, v60
	v_mov_b32_e32 v11, v60
	v_mov_b32_e32 v12, v60
	v_mov_b32_e32 v13, v60
	v_mov_b32_e32 v14, v60
	v_mov_b32_e32 v15, v60
	v_mov_b32_e32 v16, v60
	v_mov_b32_e32 v17, v60
	v_mov_b32_e32 v18, v60
	v_mov_b32_e32 v19, v60
	v_mov_b32_e32 v20, v60
	v_mov_b32_e32 v21, v60
	v_mov_b32_e32 v22, v60
	v_mov_b32_e32 v23, v60
	v_mov_b32_e32 v24, v60
	v_mov_b32_e32 v25, v60
	v_mov_b32_e32 v26, v60
	v_mov_b32_e32 v27, v60
	v_mov_b32_e32 v28, v60
	v_mov_b32_e32 v29, v60
	v_mov_b32_e32 v30, v60
	v_mov_b32_e32 v31, v60
	v_mov_b32_e32 v32, v60
	v_mov_b32_e32 v33, v60
	v_mov_b32_e32 v34, v60
	v_mov_b32_e32 v35, v60
	s_waitcnt vmcnt(22)
	v_mov_b32_e32 v36, v60
	v_mov_b32_e32 v37, v60
	v_mov_b32_e32 v38, v60
	v_mov_b32_e32 v39, v60
	s_waitcnt vmcnt(21)
	v_mov_b32_e32 v40, v60
	v_mov_b32_e32 v41, v60
	v_mov_b32_e32 v42, v60
	v_mov_b32_e32 v43, v60
	s_waitcnt vmcnt(20)
	v_mov_b32_e32 v44, v60
	v_mov_b32_e32 v45, v60
	v_mov_b32_e32 v46, v60
	v_mov_b32_e32 v47, v60
	s_waitcnt vmcnt(19)
	v_mov_b32_e32 v48, v60
	v_mov_b32_e32 v49, v60
	v_mov_b32_e32 v50, v60
	v_mov_b32_e32 v51, v60
	s_waitcnt vmcnt(18)
	v_mov_b32_e32 v52, v60
	v_mov_b32_e32 v53, v60
	v_mov_b32_e32 v54, v60
	v_mov_b32_e32 v55, v60
	v_mov_b32_e32 v56, v60
	v_mov_b32_e32 v57, v60
	v_mov_b32_e32 v58, v60
	v_mov_b32_e32 v59, v60
	v_mov_b32_e32 v64, v60
	v_mov_b32_e32 v65, v60
	v_mov_b32_e32 v66, v60
	v_mov_b32_e32 v67, v60
	v_mov_b32_e32 v68, v60
	v_mov_b32_e32 v69, v60
	v_mov_b32_e32 v70, v60
	v_mov_b32_e32 v71, v60
	v_mov_b32_e32 v72, v60
	v_mov_b32_e32 v73, v60
	v_mov_b32_e32 v74, v60
	v_mov_b32_e32 v75, v60
	v_mov_b32_e32 v76, v60
	v_mov_b32_e32 v77, v60
	v_mov_b32_e32 v78, v60
	v_mov_b32_e32 v79, v60
	v_mov_b32_e32 v80, v60
	v_mov_b32_e32 v81, v60
	v_mov_b32_e32 v82, v60
	v_mov_b32_e32 v83, v60
	v_mov_b32_e32 v84, v60
	v_mov_b32_e32 v85, v60
	v_mov_b32_e32 v86, v60
	v_mov_b32_e32 v87, v60
	v_mov_b32_e32 v88, v60
	v_mov_b32_e32 v89, v60
	v_mov_b32_e32 v90, v60
	v_mov_b32_e32 v91, v60
	v_mov_b32_e32 v92, v60
	v_mov_b32_e32 v93, v60
	v_mov_b32_e32 v94, v60
	v_mov_b32_e32 v95, v60
	v_and_b32_e32 v197, 63, v196
	v_lshrrev_b32_e32 v198, 3, v197
	v_and_b32_e32 v199, 7, v197
	v_xor_b32_e32 v199, v199, v198
	v_lshlrev_b32_e32 v199, 4, v199
	v_mul_u32_u24_e32 v198, 2048, v198
	v_add_u32_e32 v240, v198, v199
	v_add_u32_e32 v241, 65536, v240
	v_add_u32_e32 v242, 131072, v240
	v_add_u32_e32 v243, 196608, v240
	v_add_u32_e32 v244, 262144, v240
	v_add_u32_e32 v245, 327680, v240
	v_lshrrev_b32_e32 v198, 6, v196
	v_lshrrev_b32_e32 v199, 1, v198
	v_and_b32_e32 v198, 1, v198
	v_and_b32_e32 v190, 15, v197
	v_lshrrev_b32_e32 v191, 4, v197
	v_and_b32_e32 v192, 7, v190
	v_xor_b32_e32 v191, v191, v192
	v_lshlrev_b32_e32 v191, 4, v191
	v_mul_u32_u24_e32 v199, 0x60, v199
	v_add_u32_e32 v199, v199, v190
	v_lshl_add_u32 v246, v199, 7, v191
	v_xor_b32_e32 v247, 64, v246
	v_lshlrev_b32_e32 v198, 6, v198
	v_add_u32_e32 v198, v198, v190
	v_lshl_add_u32 v248, v198, 7, v191
	v_add_u32_e32 v248, 0x6000, v248
	v_xor_b32_e32 v249, 64, v248
	v_lshrrev_b32_e32 v198, 6, v196
	v_lshlrev_b32_e32 v198, 10, v198
	s_nop 0
	v_readfirstlane_b32 s8, v198
	s_waitcnt lgkmcnt(0)
	s_barrier
	s_add_u32 m0, s8, 0
	s_nop 0
	global_load_lds_dwordx4 v240, s[98:99]
	s_add_u32 m0, s8, 4096
	s_nop 0
	global_load_lds_dwordx4 v241, s[98:99]
	s_add_u32 m0, s8, 8192
	s_nop 0
	global_load_lds_dwordx4 v242, s[98:99]
	s_add_u32 m0, s8, 12288
	s_nop 0
	global_load_lds_dwordx4 v243, s[98:99]
	s_add_u32 m0, s8, 16384
	s_nop 0
	global_load_lds_dwordx4 v244, s[98:99]
	s_add_u32 m0, s8, 20480
	s_nop 0
	global_load_lds_dwordx4 v245, s[98:99]
	s_add_u32 m0, s8, 24576
	s_nop 0
	global_load_lds_dwordx4 v240, s[100:101]
	s_add_u32 m0, s8, 28672
	s_nop 0
	global_load_lds_dwordx4 v241, s[100:101]
	s_add_u32 m0, s8, 32768
	s_nop 0
	global_load_lds_dwordx4 v242, s[100:101]
	s_add_u32 m0, s8, 36864
	s_nop 0
	global_load_lds_dwordx4 v243, s[100:101]
	s_add_u32 s98, s98, 0x80
	s_addc_u32 s99, s99, 0
	s_add_u32 s100, s100, 0x80
	s_addc_u32 s101, s101, 0
	s_waitcnt vmcnt(0)
	s_barrier
	ds_read_b128 v[120:123], v248 offset:0
	ds_read_b128 v[124:127], v248 offset:2048
	ds_read_b128 v[128:131], v248 offset:4096
	ds_read_b128 v[132:135], v248 offset:6144
	ds_read_b128 v[96:99], v246 offset:0
	ds_read_b128 v[100:103], v246 offset:2048
	ds_read_b128 v[104:107], v246 offset:4096
	ds_read_b128 v[108:111], v246 offset:6144
	ds_read_b128 v[112:115], v246 offset:8192
	ds_read_b128 v[116:119], v246 offset:10240
	s_add_u32 m0, s8, 40960
	s_nop 0
	global_load_lds_dwordx4 v240, s[98:99]
	s_add_u32 m0, s8, 45056
	s_nop 0
	global_load_lds_dwordx4 v241, s[98:99]
	s_add_u32 m0, s8, 49152
	s_nop 0
	global_load_lds_dwordx4 v242, s[98:99]
	s_add_u32 m0, s8, 53248
	s_nop 0
	global_load_lds_dwordx4 v243, s[98:99]
	s_add_u32 m0, s8, 57344
	s_nop 0
	global_load_lds_dwordx4 v244, s[98:99]
	s_add_u32 m0, s8, 61440
	s_nop 0
	global_load_lds_dwordx4 v245, s[98:99]
	s_add_u32 m0, s8, 65536
	s_nop 0
	global_load_lds_dwordx4 v240, s[100:101]
	s_add_u32 m0, s8, 69632
	s_nop 0
	global_load_lds_dwordx4 v241, s[100:101]
	s_add_u32 m0, s8, 73728
	s_nop 0
	global_load_lds_dwordx4 v242, s[100:101]
	s_add_u32 m0, s8, 77824
	s_nop 0
	global_load_lds_dwordx4 v243, s[100:101]
	s_add_u32 s98, s98, 0x80
	s_addc_u32 s99, s99, 0
	s_add_u32 s100, s100, 0x80
	s_addc_u32 s101, s101, 0
	s_waitcnt lgkmcnt(0)
	v_mfma_f32_16x16x32_bf16 v[92:95], v[120:123], v[96:99], v[92:95]
	v_mfma_f32_16x16x32_bf16 v[88:91], v[124:127], v[96:99], v[88:91]
	ds_read_b128 v[224:227], v249 offset:0
	v_mfma_f32_16x16x32_bf16 v[84:87], v[128:131], v[96:99], v[84:87]
	v_mfma_f32_16x16x32_bf16 v[80:83], v[132:135], v[96:99], v[80:83]
	ds_read_b128 v[228:231], v249 offset:2048
	v_mfma_f32_16x16x32_bf16 v[76:79], v[120:123], v[100:103], v[76:79]
	v_mfma_f32_16x16x32_bf16 v[72:75], v[124:127], v[100:103], v[72:75]
	ds_read_b128 v[232:235], v249 offset:4096
	v_mfma_f32_16x16x32_bf16 v[68:71], v[128:131], v[100:103], v[68:71]
	v_mfma_f32_16x16x32_bf16 v[64:67], v[132:135], v[100:103], v[64:67]
	ds_read_b128 v[236:239], v249 offset:6144
	v_mfma_f32_16x16x32_bf16 v[56:59], v[120:123], v[104:107], v[56:59]
	v_mfma_f32_16x16x32_bf16 v[52:55], v[124:127], v[104:107], v[52:55]
	ds_read_b128 v[200:203], v247 offset:0
	v_mfma_f32_16x16x32_bf16 v[48:51], v[128:131], v[104:107], v[48:51]
	v_mfma_f32_16x16x32_bf16 v[44:47], v[132:135], v[104:107], v[44:47]
	ds_read_b128 v[204:207], v247 offset:2048
	v_mfma_f32_16x16x32_bf16 v[40:43], v[120:123], v[108:111], v[40:43]
	v_mfma_f32_16x16x32_bf16 v[36:39], v[124:127], v[108:111], v[36:39]
	ds_read_b128 v[208:211], v247 offset:4096
	v_mfma_f32_16x16x32_bf16 v[32:35], v[128:131], v[108:111], v[32:35]
	v_mfma_f32_16x16x32_bf16 v[28:31], v[132:135], v[108:111], v[28:31]
	ds_read_b128 v[212:215], v247 offset:6144
	v_mfma_f32_16x16x32_bf16 v[24:27], v[120:123], v[112:115], v[24:27]
	v_mfma_f32_16x16x32_bf16 v[20:23], v[124:127], v[112:115], v[20:23]
	ds_read_b128 v[216:219], v247 offset:8192
	v_mfma_f32_16x16x32_bf16 v[16:19], v[128:131], v[112:115], v[16:19]
	v_mfma_f32_16x16x32_bf16 v[12:15], v[132:135], v[112:115], v[12:15]
	ds_read_b128 v[220:223], v247 offset:10240
	v_mfma_f32_16x16x32_bf16 v[8:11], v[120:123], v[116:119], v[8:11]
	v_mfma_f32_16x16x32_bf16 v[4:7], v[124:127], v[116:119], v[4:7]
	v_mfma_f32_16x16x32_bf16 v[0:3], v[128:131], v[116:119], v[0:3]
	v_mfma_f32_16x16x32_bf16 v[60:63], v[132:135], v[116:119], v[60:63]
	s_mov_b32 s9, 7
